# np_xl6 + attention mid-tile loads hoisted above barrier + first grid sync replaced by two-level logical-group barrier
# speedup vs baseline: 1.0368x; 1.0093x over previous
.Lcensus_ok:
	s_mov_b32 s101, 0
	v_lshrrev_b32_e32 v1, 20, v0
	v_lshrrev_b32_e32 v0, 10, v0
	v_or_b32_e32 v0, v0, v1
	s_movk_i32 s0, 0x3ff
	v_and_or_b32 v0, v0, s0, v218
	v_cmp_eq_u32_e32 vcc, 0, v0
	s_waitcnt lgkmcnt(0)
	s_barrier
	s_and_saveexec_b64 s[0:1], vcc
	s_cbranch_execz .LBB0_138
	buffer_wbl2 sc1
	s_waitcnt vmcnt(0)
	s_and_b32 s4, s2, 7
	s_lshl_b32 s4, s4, 6
	s_add_i32 s5, s4, 0x3800
	v_mov_b32_e32 v4, s5
	v_mov_b32_e32 v5, 1
	global_atomic_add v6, v4, v5, s[38:39] sc0
	s_lshr_b32 s6, s72, 3
	s_sub_u32 s6, s6, 1
	s_waitcnt vmcnt(0)
	v_cmp_ne_u32_e32 vcc, s6, v6
	s_cbranch_vccnz .Lfs_poll
	v_mov_b32_e32 v4, 0x3a40
	global_atomic_add v6, v4, v5, s[38:39] sc0
	s_waitcnt vmcnt(0)
	v_cmp_ne_u32_e32 vcc, 7, v6
	s_cbranch_vccnz .Lfs_poll
	v_mov_b32_e32 v4, 0x3a80
	global_atomic_add v4, v5, s[38:39]
	global_atomic_add v4, v5, s[38:39] offset:64
	global_atomic_add v4, v5, s[38:39] offset:128
	global_atomic_add v4, v5, s[38:39] offset:192
	global_atomic_add v4, v5, s[38:39] offset:256
	global_atomic_add v4, v5, s[38:39] offset:320
	global_atomic_add v4, v5, s[38:39] offset:384
	global_atomic_add v4, v5, s[38:39] offset:448
.Lfs_poll:
	s_add_i32 s5, s4, 0x3a80
	v_mov_b32_e32 v4, s5
	s_mov_b32 s6, 0
.Lfs_spin:
	global_load_dword v6, v4, s[38:39] sc1
	s_waitcnt vmcnt(0)
	v_cmp_eq_u32_e32 vcc, 0, v6
	s_cbranch_vccz .Lfs_rel
	s_sleep 1
	s_add_u32 s6, s6, 1
	s_cmp_lt_u32 s6, 0x100000
	s_cbranch_scc1 .Lfs_spin
.Lfs_rel:
	buffer_inv sc1
	s_waitcnt vmcnt(0)

.LBB0_951:
	v_mov_b32_e32 v80, v199
	s_min_u32 s64, s60, s61
	v_lshrrev_b32_e32 v81, 3, v80
	v_lshlrev_b32_e32 v83, 4, v80
	v_mul_lo_u32 v82, v81, s51
	v_and_b32_e32 v84, 0x70, v83
	v_mul_lo_u32 v81, v81, s5
	v_and_b32_e32 v83, 0x60, v83
	v_lshlrev_b32_e32 v80, 3, v80
	v_and_b32_e32 v80, 8, v80
	v_add3_u32 v81, 0, v81, v83
	v_add3_u32 v80, v81, v80, s55
	s_lshl_b64 s[10:11], s[64:65], 17
	v_add3_u32 v82, 0, v82, v84
	v_add_u32_e32 v81, 0x6000, v80
	v_add_u32_e32 v80, 0x8800, v80
	s_add_u32 s10, s22, s10
	s_waitcnt vmcnt(4)
	ds_write_b128 v82, v[160:163] offset:44032
	s_waitcnt vmcnt(2)
	ds_write_b128 v82, v[176:179] offset:44160
	ds_write_b128 v82, v[164:167] offset:44288
	s_waitcnt vmcnt(0)
	ds_write2_b64 v80, v[172:173], v[174:175] offset1:2
	v_mov_b32_e32 v80, v199
	s_addc_u32 s11, s23, s11
	s_lshl_b64 s[16:17], s[64:65], 13
	ds_write2_b64 v81, v[168:169], v[170:171] offset0:128 offset1:130
	s_add_u32 s16, s26, s16
	v_lshrrev_b32_e32 v81, 3, v80
	v_lshlrev_b32_e32 v80, 4, v80
	s_addc_u32 s17, s27, s17
	s_lshl_b64 s[40:41], s[64:65], 7
	v_and_b32_e32 v80, 0x70, v80
	s_add_u32 s40, s24, s40
	v_lshl_or_b32 v180, v81, 12, v80
	s_addc_u32 s41, s25, s41
	v_lshl_or_b32 v82, v81, 11, v80
	v_lshl_or_b32 v83, v81, 7, v80
	v_lshl_add_u64 v[80:81], s[40:41], 0, v[180:181]
	v_add_co_u32_e32 v80, vcc, 0x40000, v80
	global_load_dwordx4 v[168:171], v82, s[10:11]
	global_load_dwordx4 v[172:175], v82, s[10:11] offset:128
	global_load_dwordx4 v[160:163], v180, s[40:41]
	v_addc_co_u32_e32 v81, vcc, 0, v81, vcc
	global_load_dwordx4 v[176:179], v83, s[16:17]
	global_load_dwordx4 v[164:167], v[80:81], off
	s_waitcnt lgkmcnt(0)
	s_barrier
	s_add_i32 s10, s62, 1
	s_cmp_gt_i32 s10, s59
	s_cbranch_scc1 .LBB0_957
	ds_read_b128 v[80:83], v205 offset:44032
	ds_read_b128 v[210:213], v205 offset:44064
	ds_read_b128 v[214:217], v205 offset:56832
	ds_read_b128 v[220:223], v205 offset:56864
	s_waitcnt lgkmcnt(3)
	v_mfma_f32_32x32x16_bf16 v[96:111], v[80:83], v[112:115], v[64:79]
	s_waitcnt lgkmcnt(1)
	v_mfma_f32_32x32x16_bf16 v[80:95], v[214:217], v[112:115], v[64:79]
	ds_read_b128 v[214:217], v205 offset:44096
	ds_read_b128 v[224:227], v205 offset:56896
	v_mfma_f32_32x32x16_bf16 v[96:111], v[210:213], v[116:119], v[96:111]
	s_waitcnt lgkmcnt(2)
	v_mfma_f32_32x32x16_bf16 v[80:95], v[220:223], v[116:119], v[80:95]
	ds_read_b128 v[210:213], v205 offset:44128
	ds_read_b128 v[220:223], v205 offset:56928
	s_waitcnt lgkmcnt(3)
	v_mfma_f32_32x32x16_bf16 v[96:111], v[214:217], v[120:123], v[96:111]
	s_waitcnt lgkmcnt(2)
	v_mfma_f32_32x32x16_bf16 v[80:95], v[224:227], v[120:123], v[80:95]
	ds_read_b128 v[214:217], v205 offset:44160
	ds_read_b128 v[224:227], v205 offset:56960
	s_waitcnt lgkmcnt(3)
	v_mfma_f32_32x32x16_bf16 v[96:111], v[210:213], v[124:127], v[96:111]
	s_waitcnt lgkmcnt(2)
	v_mfma_f32_32x32x16_bf16 v[80:95], v[220:223], v[124:127], v[80:95]
	ds_read_b128 v[210:213], v205 offset:44192
	ds_read_b128 v[220:223], v205 offset:56992
	s_waitcnt lgkmcnt(3)
	v_mfma_f32_32x32x16_bf16 v[96:111], v[214:217], v[128:131], v[96:111]
	s_waitcnt lgkmcnt(2)
	v_mfma_f32_32x32x16_bf16 v[80:95], v[224:227], v[128:131], v[80:95]
	ds_read_b128 v[214:217], v205 offset:44224
	ds_read_b128 v[224:227], v205 offset:57024
	s_waitcnt lgkmcnt(3)
	v_mfma_f32_32x32x16_bf16 v[96:111], v[210:213], v[132:135], v[96:111]
	s_waitcnt lgkmcnt(2)
	v_mfma_f32_32x32x16_bf16 v[80:95], v[220:223], v[132:135], v[80:95]
	ds_read_b128 v[210:213], v205 offset:44256
	ds_read_b128 v[220:223], v205 offset:57056
	s_waitcnt lgkmcnt(3)
	v_mfma_f32_32x32x16_bf16 v[96:111], v[214:217], v[136:139], v[96:111]
	s_waitcnt lgkmcnt(2)
	v_mfma_f32_32x32x16_bf16 v[80:95], v[224:227], v[136:139], v[80:95]
	ds_read_b128 v[214:217], v205 offset:44288
	ds_read_b128 v[224:227], v205 offset:57088
	s_waitcnt lgkmcnt(3)
	v_mfma_f32_32x32x16_bf16 v[96:111], v[210:213], v[140:143], v[96:111]
	s_waitcnt lgkmcnt(2)
	v_mfma_f32_32x32x16_bf16 v[80:95], v[220:223], v[140:143], v[80:95]
	ds_read_b128 v[210:213], v205 offset:44320
	ds_read_b128 v[220:223], v205 offset:57120
	s_waitcnt lgkmcnt(3)
	v_mfma_f32_32x32x16_bf16 v[96:111], v[214:217], v[144:147], v[96:111]
	s_waitcnt lgkmcnt(2)
	v_mfma_f32_32x32x16_bf16 v[80:95], v[224:227], v[144:147], v[80:95]
	ds_read_b128 v[214:217], v205 offset:44352
	ds_read_b128 v[224:227], v205 offset:57152
	s_waitcnt lgkmcnt(3)
	v_mfma_f32_32x32x16_bf16 v[96:111], v[210:213], v[148:151], v[96:111]
	s_waitcnt lgkmcnt(2)
	v_mfma_f32_32x32x16_bf16 v[80:95], v[220:223], v[148:151], v[80:95]
	ds_read_b128 v[210:213], v205 offset:44384
	ds_read_b128 v[220:223], v205 offset:57184
	s_waitcnt lgkmcnt(3)
	v_mfma_f32_32x32x16_bf16 v[96:111], v[214:217], v[152:155], v[96:111]
	s_waitcnt lgkmcnt(2)
	v_mfma_f32_32x32x16_bf16 v[80:95], v[224:227], v[152:155], v[80:95]
	s_waitcnt lgkmcnt(1)
	v_mfma_f32_32x32x16_bf16 v[96:111], v[210:213], v[156:159], v[96:111]
	s_waitcnt lgkmcnt(0)
	v_mfma_f32_32x32x16_bf16 v[80:95], v[220:223], v[156:159], v[80:95]
	s_add_i32 s10, s62, 64
	s_cmp_le_i32 s10, s57
	s_nop 15
	s_nop 7
	s_cbranch_scc1 .LBB0_954
	v_add_u32_e32 v180, s62, v197
	v_add_u32_e32 v203, 33, v180
	v_add_u32_e32 v202, 1, v180
	v_cmp_le_i32_e32 vcc, v203, v196
	s_nop 4
	v_cndmask_b32_e32 v80, v204, v80, vcc
	v_cmp_lt_i32_e32 vcc, v202, v196
	s_nop 1
	v_cndmask_b32_e32 v97, v204, v97, vcc
	v_cmp_le_i32_e32 vcc, v202, v196
	v_add_u32_e32 v202, 34, v180
	s_nop 0
	v_cndmask_b32_e32 v96, v204, v96, vcc
	v_cmp_le_i32_e32 vcc, v202, v196
	v_add_u32_e32 v202, 3, v180
	s_nop 0
	v_cndmask_b32_e32 v81, v204, v81, vcc
	v_cmp_le_i32_e32 vcc, v202, v196
	v_add_u32_e32 v202, 35, v180
	s_nop 0
	v_cndmask_b32_e32 v98, v204, v98, vcc
	v_cmp_le_i32_e32 vcc, v202, v196
	v_add_u32_e32 v202, 4, v180
	s_nop 0
	v_cndmask_b32_e32 v82, v204, v82, vcc
	v_cmp_le_i32_e32 vcc, v202, v196
	v_add_u32_e32 v202, 36, v180
	s_nop 0
	v_cndmask_b32_e32 v99, v204, v99, vcc
	v_cmp_le_i32_e32 vcc, v202, v196
	v_add_u32_e32 v202, 9, v180
	s_nop 0
	v_cndmask_b32_e32 v83, v204, v83, vcc
	v_cmp_le_i32_e32 vcc, v202, v196
	v_add_u32_e32 v202, 41, v180
	s_nop 0
	v_cndmask_b32_e32 v100, v204, v100, vcc
	v_cmp_le_i32_e32 vcc, v202, v196
	v_add_u32_e32 v202, 10, v180
	s_nop 0
	v_cndmask_b32_e32 v84, v204, v84, vcc
	v_cmp_le_i32_e32 vcc, v202, v196
	v_add_u32_e32 v202, 42, v180
	s_nop 0
	v_cndmask_b32_e32 v101, v204, v101, vcc
	v_cmp_le_i32_e32 vcc, v202, v196
	v_add_u32_e32 v202, 11, v180
	s_nop 0
	v_cndmask_b32_e32 v85, v204, v85, vcc
	v_cmp_le_i32_e32 vcc, v202, v196
	v_add_u32_e32 v202, 43, v180
	s_nop 0
	v_cndmask_b32_e32 v102, v204, v102, vcc
	v_cmp_le_i32_e32 vcc, v202, v196
	v_add_u32_e32 v202, 12, v180
	s_nop 0
	v_cndmask_b32_e32 v86, v204, v86, vcc
	v_cmp_le_i32_e32 vcc, v202, v196
	v_add_u32_e32 v202, 44, v180
	s_nop 0
	v_cndmask_b32_e32 v103, v204, v103, vcc
	v_cmp_le_i32_e32 vcc, v202, v196
	v_add_u32_e32 v202, 17, v180
	s_nop 0
	v_cndmask_b32_e32 v87, v204, v87, vcc
	v_cmp_le_i32_e32 vcc, v202, v196
	v_add_u32_e32 v202, 49, v180
	s_nop 0
	v_cndmask_b32_e32 v104, v204, v104, vcc
	v_cmp_le_i32_e32 vcc, v202, v196
	v_add_u32_e32 v202, 18, v180
	s_nop 0
	v_cndmask_b32_e32 v88, v204, v88, vcc
	v_cmp_le_i32_e32 vcc, v202, v196
	v_add_u32_e32 v202, 50, v180
	s_nop 0
	v_cndmask_b32_e32 v105, v204, v105, vcc
	v_cmp_le_i32_e32 vcc, v202, v196
	v_add_u32_e32 v202, 19, v180
	s_nop 0
	v_cndmask_b32_e32 v89, v204, v89, vcc
	v_cmp_le_i32_e32 vcc, v202, v196
	v_add_u32_e32 v202, 51, v180
	s_nop 0
	v_cndmask_b32_e32 v106, v204, v106, vcc
	v_cmp_le_i32_e32 vcc, v202, v196
	v_add_u32_e32 v202, 20, v180
	s_nop 0
	v_cndmask_b32_e32 v90, v204, v90, vcc
	v_cmp_le_i32_e32 vcc, v202, v196
	v_add_u32_e32 v202, 52, v180
	s_nop 0
	v_cndmask_b32_e32 v107, v204, v107, vcc
	v_cmp_le_i32_e32 vcc, v202, v196
	v_add_u32_e32 v202, 25, v180
	s_nop 0
	v_cndmask_b32_e32 v91, v204, v91, vcc
	v_cmp_le_i32_e32 vcc, v202, v196
	v_add_u32_e32 v202, 57, v180
	s_nop 0
	v_cndmask_b32_e32 v108, v204, v108, vcc
	v_cmp_le_i32_e32 vcc, v202, v196
	v_add_u32_e32 v202, 26, v180
	s_nop 0
	v_cndmask_b32_e32 v92, v204, v92, vcc
	v_cmp_le_i32_e32 vcc, v202, v196
	v_add_u32_e32 v202, 58, v180
	s_nop 0
	v_cndmask_b32_e32 v109, v204, v109, vcc
	v_cmp_le_i32_e32 vcc, v202, v196
	v_add_u32_e32 v202, 27, v180
	s_nop 0
	v_cndmask_b32_e32 v93, v204, v93, vcc
	v_cmp_le_i32_e32 vcc, v202, v196
	v_add_u32_e32 v202, 59, v180
	s_nop 0
	v_cndmask_b32_e32 v110, v204, v110, vcc
	v_cmp_le_i32_e32 vcc, v202, v196
	v_add_u32_e32 v202, 28, v180
	v_add_u32_e32 v180, 60, v180
	v_cndmask_b32_e32 v94, v204, v94, vcc
	v_cmp_le_i32_e32 vcc, v202, v196
	s_nop 1
	v_cndmask_b32_e32 v111, v204, v111, vcc
	v_cmp_le_i32_e32 vcc, v180, v196
	s_nop 1
	v_cndmask_b32_e32 v95, v204, v95, vcc

.LBB0_973:
	v_mov_b32_e32 v80, v195
	s_min_u32 s64, s36, s39
	v_lshrrev_b32_e32 v81, 3, v80
	v_lshlrev_b32_e32 v83, 4, v80
	v_mul_lo_u32 v82, v81, s51
	v_and_b32_e32 v84, 0x70, v83
	v_mul_lo_u32 v81, v81, s5
	v_and_b32_e32 v83, 0x60, v83
	v_lshlrev_b32_e32 v80, 3, v80
	v_and_b32_e32 v80, 8, v80
	v_add3_u32 v81, 0, v81, v83
	v_add3_u32 v80, v81, v80, s55
	s_lshl_b64 s[10:11], s[64:65], 17
	v_add3_u32 v82, 0, v82, v84
	v_add_u32_e32 v81, 0x6000, v80
	v_add_u32_e32 v80, 0x8800, v80
	s_add_u32 s10, s22, s10
	s_waitcnt vmcnt(4)
	ds_write_b128 v82, v[160:163] offset:44032
	s_waitcnt vmcnt(2)
	ds_write_b128 v82, v[176:179] offset:44160
	ds_write_b128 v82, v[164:167] offset:44288
	s_waitcnt vmcnt(0)
	ds_write2_b64 v80, v[172:173], v[174:175] offset1:2
	v_mov_b32_e32 v80, v195
	s_addc_u32 s11, s23, s11
	s_lshl_b64 s[16:17], s[64:65], 13
	ds_write2_b64 v81, v[168:169], v[170:171] offset0:128 offset1:130
	s_add_u32 s16, s26, s16
	v_lshrrev_b32_e32 v81, 3, v80
	v_lshlrev_b32_e32 v80, 4, v80
	s_addc_u32 s17, s27, s17
	s_lshl_b64 s[30:31], s[64:65], 7
	v_and_b32_e32 v80, 0x70, v80
	s_add_u32 s30, s24, s30
	v_lshl_or_b32 v180, v81, 12, v80
	s_addc_u32 s31, s25, s31
	v_lshl_or_b32 v82, v81, 11, v80
	v_lshl_or_b32 v83, v81, 7, v80
	v_lshl_add_u64 v[80:81], s[30:31], 0, v[180:181]
	v_add_co_u32_e32 v80, vcc, 0x40000, v80
	global_load_dwordx4 v[168:171], v82, s[10:11]
	global_load_dwordx4 v[172:175], v82, s[10:11] offset:128
	global_load_dwordx4 v[160:163], v180, s[30:31]
	v_addc_co_u32_e32 v81, vcc, 0, v81, vcc
	global_load_dwordx4 v[176:179], v83, s[16:17]
	global_load_dwordx4 v[164:167], v[80:81], off
	s_waitcnt lgkmcnt(0)
	s_barrier
	s_add_i32 s10, s40, 1
	s_cmp_gt_i32 s10, s38
	s_cbranch_scc1 .LBB0_979
	ds_read_b128 v[80:83], v207 offset:44032
	ds_read_b128 v[212:215], v207 offset:44064
	ds_read_b128 v[220:223], v207 offset:56832
	ds_read_b128 v[224:227], v207 offset:56864
	s_waitcnt lgkmcnt(3)
	v_mfma_f32_32x32x16_bf16 v[96:111], v[80:83], v[112:115], v[64:79]
	s_waitcnt lgkmcnt(1)
	v_mfma_f32_32x32x16_bf16 v[80:95], v[220:223], v[112:115], v[64:79]
	ds_read_b128 v[220:223], v207 offset:44096
	ds_read_b128 v[228:231], v207 offset:56896
	v_mfma_f32_32x32x16_bf16 v[96:111], v[212:215], v[116:119], v[96:111]
	s_waitcnt lgkmcnt(2)
	v_mfma_f32_32x32x16_bf16 v[80:95], v[224:227], v[116:119], v[80:95]
	ds_read_b128 v[212:215], v207 offset:44128
	ds_read_b128 v[224:227], v207 offset:56928
	s_waitcnt lgkmcnt(3)
	v_mfma_f32_32x32x16_bf16 v[96:111], v[220:223], v[120:123], v[96:111]
	s_waitcnt lgkmcnt(2)
	v_mfma_f32_32x32x16_bf16 v[80:95], v[228:231], v[120:123], v[80:95]
	ds_read_b128 v[220:223], v207 offset:44160
	ds_read_b128 v[228:231], v207 offset:56960
	s_waitcnt lgkmcnt(3)
	v_mfma_f32_32x32x16_bf16 v[96:111], v[212:215], v[124:127], v[96:111]
	s_waitcnt lgkmcnt(2)
	v_mfma_f32_32x32x16_bf16 v[80:95], v[224:227], v[124:127], v[80:95]
	ds_read_b128 v[212:215], v207 offset:44192
	ds_read_b128 v[224:227], v207 offset:56992
	s_waitcnt lgkmcnt(3)
	v_mfma_f32_32x32x16_bf16 v[96:111], v[220:223], v[128:131], v[96:111]
	s_waitcnt lgkmcnt(2)
	v_mfma_f32_32x32x16_bf16 v[80:95], v[228:231], v[128:131], v[80:95]
	ds_read_b128 v[220:223], v207 offset:44224
	ds_read_b128 v[228:231], v207 offset:57024
	s_waitcnt lgkmcnt(3)
	v_mfma_f32_32x32x16_bf16 v[96:111], v[212:215], v[132:135], v[96:111]
	s_waitcnt lgkmcnt(2)
	v_mfma_f32_32x32x16_bf16 v[80:95], v[224:227], v[132:135], v[80:95]
	ds_read_b128 v[212:215], v207 offset:44256
	ds_read_b128 v[224:227], v207 offset:57056
	s_waitcnt lgkmcnt(3)
	v_mfma_f32_32x32x16_bf16 v[96:111], v[220:223], v[136:139], v[96:111]
	s_waitcnt lgkmcnt(2)
	v_mfma_f32_32x32x16_bf16 v[80:95], v[228:231], v[136:139], v[80:95]
	ds_read_b128 v[220:223], v207 offset:44288
	ds_read_b128 v[228:231], v207 offset:57088
	s_waitcnt lgkmcnt(3)
	v_mfma_f32_32x32x16_bf16 v[96:111], v[212:215], v[140:143], v[96:111]
	s_waitcnt lgkmcnt(2)
	v_mfma_f32_32x32x16_bf16 v[80:95], v[224:227], v[140:143], v[80:95]
	ds_read_b128 v[212:215], v207 offset:44320
	ds_read_b128 v[224:227], v207 offset:57120
	s_waitcnt lgkmcnt(3)
	v_mfma_f32_32x32x16_bf16 v[96:111], v[220:223], v[144:147], v[96:111]
	s_waitcnt lgkmcnt(2)
	v_mfma_f32_32x32x16_bf16 v[80:95], v[228:231], v[144:147], v[80:95]
	ds_read_b128 v[220:223], v207 offset:44352
	ds_read_b128 v[228:231], v207 offset:57152
	s_waitcnt lgkmcnt(3)
	v_mfma_f32_32x32x16_bf16 v[96:111], v[212:215], v[148:151], v[96:111]
	s_waitcnt lgkmcnt(2)
	v_mfma_f32_32x32x16_bf16 v[80:95], v[224:227], v[148:151], v[80:95]
	ds_read_b128 v[212:215], v207 offset:44384
	ds_read_b128 v[224:227], v207 offset:57184
	s_waitcnt lgkmcnt(3)
	v_mfma_f32_32x32x16_bf16 v[96:111], v[220:223], v[152:155], v[96:111]
	s_waitcnt lgkmcnt(2)
	v_mfma_f32_32x32x16_bf16 v[80:95], v[228:231], v[152:155], v[80:95]
	s_waitcnt lgkmcnt(1)
	v_mfma_f32_32x32x16_bf16 v[96:111], v[212:215], v[156:159], v[96:111]
	s_waitcnt lgkmcnt(0)
	v_mfma_f32_32x32x16_bf16 v[80:95], v[224:227], v[156:159], v[80:95]
	s_add_i32 s10, s40, 64
	s_cmp_le_i32 s10, s1
	s_nop 15
	s_nop 7
	s_cbranch_scc1 .LBB0_976
	v_add_u32_e32 v180, s40, v199
	v_add_u32_e32 v203, 33, v180
	v_add_u32_e32 v202, 1, v180
	v_cmp_le_i32_e32 vcc, v203, v198
	s_nop 4
	v_cndmask_b32_e32 v80, v204, v80, vcc
	v_cmp_lt_i32_e32 vcc, v202, v198
	s_nop 1
	v_cndmask_b32_e32 v97, v204, v97, vcc
	v_cmp_le_i32_e32 vcc, v202, v198
	v_add_u32_e32 v202, 34, v180
	s_nop 0
	v_cndmask_b32_e32 v96, v204, v96, vcc
	v_cmp_le_i32_e32 vcc, v202, v198
	v_add_u32_e32 v202, 3, v180
	s_nop 0
	v_cndmask_b32_e32 v81, v204, v81, vcc
	v_cmp_le_i32_e32 vcc, v202, v198
	v_add_u32_e32 v202, 35, v180
	s_nop 0
	v_cndmask_b32_e32 v98, v204, v98, vcc
	v_cmp_le_i32_e32 vcc, v202, v198
	v_add_u32_e32 v202, 4, v180
	s_nop 0
	v_cndmask_b32_e32 v82, v204, v82, vcc
	v_cmp_le_i32_e32 vcc, v202, v198
	v_add_u32_e32 v202, 36, v180
	s_nop 0
	v_cndmask_b32_e32 v99, v204, v99, vcc
	v_cmp_le_i32_e32 vcc, v202, v198
	v_add_u32_e32 v202, 9, v180
	s_nop 0
	v_cndmask_b32_e32 v83, v204, v83, vcc
	v_cmp_le_i32_e32 vcc, v202, v198
	v_add_u32_e32 v202, 41, v180
	s_nop 0
	v_cndmask_b32_e32 v100, v204, v100, vcc
	v_cmp_le_i32_e32 vcc, v202, v198
	v_add_u32_e32 v202, 10, v180
	s_nop 0
	v_cndmask_b32_e32 v84, v204, v84, vcc
	v_cmp_le_i32_e32 vcc, v202, v198
	v_add_u32_e32 v202, 42, v180
	s_nop 0
	v_cndmask_b32_e32 v101, v204, v101, vcc
	v_cmp_le_i32_e32 vcc, v202, v198
	v_add_u32_e32 v202, 11, v180
	s_nop 0
	v_cndmask_b32_e32 v85, v204, v85, vcc
	v_cmp_le_i32_e32 vcc, v202, v198
	v_add_u32_e32 v202, 43, v180
	s_nop 0
	v_cndmask_b32_e32 v102, v204, v102, vcc
	v_cmp_le_i32_e32 vcc, v202, v198
	v_add_u32_e32 v202, 12, v180
	s_nop 0
	v_cndmask_b32_e32 v86, v204, v86, vcc
	v_cmp_le_i32_e32 vcc, v202, v198
	v_add_u32_e32 v202, 44, v180
	s_nop 0
	v_cndmask_b32_e32 v103, v204, v103, vcc
	v_cmp_le_i32_e32 vcc, v202, v198
	v_add_u32_e32 v202, 17, v180
	s_nop 0
	v_cndmask_b32_e32 v87, v204, v87, vcc
	v_cmp_le_i32_e32 vcc, v202, v198
	v_add_u32_e32 v202, 49, v180
	s_nop 0
	v_cndmask_b32_e32 v104, v204, v104, vcc
	v_cmp_le_i32_e32 vcc, v202, v198
	v_add_u32_e32 v202, 18, v180
	s_nop 0
	v_cndmask_b32_e32 v88, v204, v88, vcc
	v_cmp_le_i32_e32 vcc, v202, v198
	v_add_u32_e32 v202, 50, v180
	s_nop 0
	v_cndmask_b32_e32 v105, v204, v105, vcc
	v_cmp_le_i32_e32 vcc, v202, v198
	v_add_u32_e32 v202, 19, v180
	s_nop 0
	v_cndmask_b32_e32 v89, v204, v89, vcc
	v_cmp_le_i32_e32 vcc, v202, v198
	v_add_u32_e32 v202, 51, v180
	s_nop 0
	v_cndmask_b32_e32 v106, v204, v106, vcc
	v_cmp_le_i32_e32 vcc, v202, v198
	v_add_u32_e32 v202, 20, v180
	s_nop 0
	v_cndmask_b32_e32 v90, v204, v90, vcc
	v_cmp_le_i32_e32 vcc, v202, v198
	v_add_u32_e32 v202, 52, v180
	s_nop 0
	v_cndmask_b32_e32 v107, v204, v107, vcc
	v_cmp_le_i32_e32 vcc, v202, v198
	v_add_u32_e32 v202, 25, v180
	s_nop 0
	v_cndmask_b32_e32 v91, v204, v91, vcc
	v_cmp_le_i32_e32 vcc, v202, v198
	v_add_u32_e32 v202, 57, v180
	s_nop 0
	v_cndmask_b32_e32 v108, v204, v108, vcc
	v_cmp_le_i32_e32 vcc, v202, v198
	v_add_u32_e32 v202, 26, v180
	s_nop 0
	v_cndmask_b32_e32 v92, v204, v92, vcc
	v_cmp_le_i32_e32 vcc, v202, v198
	v_add_u32_e32 v202, 58, v180
	s_nop 0
	v_cndmask_b32_e32 v109, v204, v109, vcc
	v_cmp_le_i32_e32 vcc, v202, v198
	v_add_u32_e32 v202, 27, v180
	s_nop 0
	v_cndmask_b32_e32 v93, v204, v93, vcc
	v_cmp_le_i32_e32 vcc, v202, v198
	v_add_u32_e32 v202, 59, v180
	s_nop 0
	v_cndmask_b32_e32 v110, v204, v110, vcc
	v_cmp_le_i32_e32 vcc, v202, v198
	v_add_u32_e32 v202, 28, v180
	v_add_u32_e32 v180, 60, v180
	v_cndmask_b32_e32 v94, v204, v94, vcc
	v_cmp_le_i32_e32 vcc, v202, v198
	s_nop 1
	v_cndmask_b32_e32 v111, v204, v111, vcc
	v_cmp_le_i32_e32 vcc, v180, v198
	s_nop 1
	v_cndmask_b32_e32 v95, v204, v95, vcc
